# nt hint on the read-once f32 weight loads of the P0 weight-copy transposes (102 dword loads), on top of nt x loads + static prio raise
# speedup vs baseline: 1.0116x; 1.0013x over previous
.LBB0_776:
	s_ashr_i32 s0, s6, 7
	s_ashr_i32 s1, s0, 31
	s_lshl_b64 s[8:9], s[0:1], 20
	s_add_u32 s8, s56, s8
	s_addc_u32 s9, s57, s9
	s_lshl_b64 s[0:1], s[0:1], 19
	s_add_u32 s0, s20, s0
	s_addc_u32 s1, s28, s1
	s_lshl_b32 s7, s6, 2
	s_and_b32 s7, s7, 0x1c0
	v_or_b32_e32 v10, s7, v45
	s_and_b32 s10, s5, 0x1e0
	v_lshlrev_b32_e32 v10, 9, v10
	v_or3_b32 v10, v10, v44, s10
	v_lshlrev_b32_e32 v138, 2, v10
	v_lshl_add_u64 v[12:13], s[8:9], 0, v[138:139]
	v_add_co_u32_e32 v14, vcc, s68, v12
	s_lshl_b32 s7, s7, 5
	s_nop 0
	v_addc_co_u32_e32 v15, vcc, 0, v13, vcc
	v_add_co_u32_e32 v16, vcc, s69, v12
	s_add_u32 s0, s0, s7
	s_nop 0
	v_addc_co_u32_e32 v17, vcc, 0, v13, vcc
	v_add_co_u32_e32 v18, vcc, s70, v12
	s_waitcnt lgkmcnt(0)
	v_mov_b32_e32 v7, v139
	v_addc_co_u32_e32 v19, vcc, 0, v13, vcc
	v_add_co_u32_e32 v20, vcc, s19, v12
	s_addc_u32 s1, s1, 0
	s_nop 0
	v_addc_co_u32_e32 v21, vcc, 0, v13, vcc
	v_add_co_u32_e32 v22, vcc, s16, v12
	v_lshrrev_b32_e32 v76, 6, v6
	v_and_b32_e32 v78, 0x30, v6
	v_lshlrev_b32_e32 v76, 10, v76
	v_mov_b32_e32 v77, 0
	v_or_b32_e32 v76, v76, v78
	v_lshl_add_u64 v[10:11], s[0:1], 0, v[76:77]
	s_nop 0
	v_addc_co_u32_e32 v23, vcc, 0, v13, vcc
	v_add_co_u32_e32 v24, vcc, s27, v12
	s_mov_b32 s0, 0x1f000
	s_nop 0
	v_addc_co_u32_e32 v25, vcc, 0, v13, vcc
	v_add_co_u32_e32 v26, vcc, s22, v12
	global_load_dword v7, v138, s[8:9]
	s_nop 0
	v_addc_co_u32_e32 v27, vcc, 0, v13, vcc
	v_add_co_u32_e32 v28, vcc, s24, v12
	v_or_b32_e32 v62, s10, v46
	s_nop 0
	v_addc_co_u32_e32 v29, vcc, 0, v13, vcc
	v_add_co_u32_e32 v30, vcc, s29, v12
	v_or_b32_e32 v63, s10, v47
	s_nop 0
	v_addc_co_u32_e32 v31, vcc, 0, v13, vcc
	v_add_co_u32_e32 v32, vcc, s18, v12
	v_lshrrev_b32_e32 v138, 4, v62
	v_and_b32_e32 v78, 15, v62
	v_lshlrev_b32_e32 v138, 14, v138
	v_lshl_or_b32 v138, v78, 6, v138
	s_nop 0
	v_addc_co_u32_e32 v33, vcc, 0, v13, vcc
	v_add_co_u32_e32 v34, vcc, s25, v12
	v_or_b32_e32 v64, s10, v48
	s_nop 0
	v_addc_co_u32_e32 v35, vcc, 0, v13, vcc
	v_add_co_u32_e32 v36, vcc, s30, v12
	v_add_u32_e32 v55, 0x400, v53
	s_nop 0
	v_addc_co_u32_e32 v37, vcc, 0, v13, vcc
	v_add_co_u32_e32 v38, vcc, s23, v12
	v_add_u32_e32 v56, 0x800, v53
	s_nop 0
	v_addc_co_u32_e32 v39, vcc, 0, v13, vcc
	v_add_co_u32_e32 v40, vcc, s17, v12
	v_add_u32_e32 v57, 0xc00, v53
	s_nop 0
	v_addc_co_u32_e32 v41, vcc, 0, v13, vcc
	v_add_co_u32_e32 v42, vcc, s90, v12
	v_add_u32_e32 v58, 0x1000, v53
	s_nop 0
	v_addc_co_u32_e32 v43, vcc, 0, v13, vcc
	v_add_co_u32_e32 v12, vcc, s0, v12
	v_add_u32_e32 v59, 0x1400, v53
	s_nop 0
	v_addc_co_u32_e32 v13, vcc, 0, v13, vcc
	global_load_dword v66, v[14:15], off offset:-4096 nt
	s_nop 0
	global_load_dword v14, v[14:15], off nt
	s_nop 0
	global_load_dword v15, v[16:17], off offset:-4096 nt
	s_nop 0
	global_load_dword v16, v[16:17], off nt
	s_nop 0
	global_load_dword v17, v[18:19], off offset:-4096 nt
	s_nop 0
	global_load_dword v18, v[18:19], off nt
	s_nop 0
	global_load_dword v19, v[20:21], off offset:-4096 nt
	s_nop 0
	global_load_dword v20, v[20:21], off nt
	s_nop 0
	global_load_dword v21, v[22:23], off offset:-4096 nt
	s_nop 0
	global_load_dword v22, v[22:23], off nt
	s_nop 0
	global_load_dword v23, v[24:25], off offset:-4096 nt
	s_nop 0
	global_load_dword v24, v[24:25], off nt
	s_nop 0
	global_load_dword v25, v[26:27], off offset:-4096 nt
	global_load_dword v67, v[26:27], off nt
	global_load_dword v68, v[28:29], off offset:-4096 nt
	global_load_dword v69, v[28:29], off nt
	global_load_dword v70, v[30:31], off offset:-4096 nt
	global_load_dword v71, v[30:31], off nt
	global_load_dword v72, v[32:33], off offset:-4096 nt
	global_load_dword v73, v[32:33], off nt
	global_load_dword v74, v[34:35], off offset:-4096 nt
	s_nop 0
	global_load_dword v34, v[34:35], off nt
	s_nop 0
	global_load_dword v35, v[36:37], off offset:-4096 nt
	s_nop 0
	global_load_dword v36, v[36:37], off nt
	s_nop 0
	global_load_dword v37, v[38:39], off offset:-4096 nt
	s_nop 0
	global_load_dword v38, v[38:39], off nt
	s_nop 0
	global_load_dword v39, v[40:41], off offset:-4096 nt
	s_nop 0
	global_load_dword v40, v[40:41], off nt
	s_nop 0
	global_load_dword v41, v[42:43], off offset:-4096 nt
	s_nop 0
	global_load_dword v42, v[42:43], off nt
	s_nop 0
	global_load_dword v12, v[12:13], off nt
	v_lshl_add_u64 v[26:27], v[10:11], 0, v[138:139]
	v_lshrrev_b32_e32 v138, 4, v63
	v_and_b32_e32 v78, 15, v63
	v_lshlrev_b32_e32 v138, 14, v138
	v_lshl_or_b32 v138, v78, 6, v138
	v_add_u32_e32 v60, 0x1800, v53
	v_add_u32_e32 v61, 0x1c00, v53
	v_or_b32_e32 v65, s10, v49
	v_lshl_add_u64 v[28:29], v[10:11], 0, v[138:139]
	v_lshrrev_b32_e32 v138, 4, v64
	v_and_b32_e32 v78, 15, v64
	v_lshlrev_b32_e32 v138, 14, v138
	v_lshl_or_b32 v138, v78, 6, v138
	v_lshl_add_u64 v[30:31], v[10:11], 0, v[138:139]
	v_lshrrev_b32_e32 v138, 4, v65
	v_and_b32_e32 v78, 15, v65
	v_lshlrev_b32_e32 v138, 14, v138
	v_lshl_or_b32 v138, v78, 6, v138
	v_lshl_add_u64 v[32:33], v[10:11], 0, v[138:139]
	s_add_i32 s6, s6, s12
	s_add_i32 s5, s5, s96
	s_cmpk_gt_i32 s6, 0x1ff
	s_waitcnt vmcnt(0)
	ds_write2_b32 v53, v7, v66 offset1:66
	ds_write2_b32 v53, v14, v15 offset0:132 offset1:198
	ds_write2_b32 v55, v16, v17 offset0:8 offset1:74
	ds_write2_b32 v55, v18, v19 offset0:140 offset1:206
	ds_write2_b32 v56, v20, v21 offset0:16 offset1:82
	ds_write2_b32 v56, v22, v23 offset0:148 offset1:214
	ds_write2_b32 v57, v24, v25 offset0:24 offset1:90
	ds_write2_b32 v57, v67, v68 offset0:156 offset1:222
	ds_write2_b32 v58, v69, v70 offset0:32 offset1:98
	ds_write2_b32 v58, v71, v72 offset0:164 offset1:230
	ds_write2_b32 v59, v73, v74 offset0:40 offset1:106
	ds_write2_b32 v59, v34, v35 offset0:172 offset1:238
	ds_write2_b32 v60, v36, v37 offset0:48 offset1:114
	ds_write2_b32 v60, v38, v39 offset0:180 offset1:246
	ds_write2_b32 v61, v40, v41 offset0:56 offset1:122
	ds_write2_b32 v61, v42, v12 offset0:188 offset1:254
	s_waitcnt lgkmcnt(0)
	ds_read2_b32 v[10:11], v52 offset0:33 offset1:41
	ds_read2_b32 v[12:13], v52 offset1:8
	ds_read2_b32 v[14:15], v52 offset0:66 offset1:74
	ds_read2_b32 v[16:17], v52 offset0:99 offset1:107
	ds_read2_b32 v[18:19], v52 offset0:132 offset1:140
	ds_read2_b32 v[20:21], v52 offset0:165 offset1:173
	ds_read2_b32 v[22:23], v52 offset0:198 offset1:206
	ds_read2_b32 v[24:25], v52 offset0:231 offset1:239
	ds_read2_b32 v[34:35], v52 offset0:49 offset1:57
	ds_read2_b32 v[36:37], v52 offset0:16 offset1:24
	ds_read2_b32 v[38:39], v52 offset0:82 offset1:90
	ds_read2_b32 v[40:41], v52 offset0:115 offset1:123
	ds_read2_b32 v[42:43], v52 offset0:148 offset1:156
	ds_read2_b32 v[56:57], v52 offset0:181 offset1:189
	ds_read2_b32 v[58:59], v52 offset0:214 offset1:222
	ds_read2_b32 v[60:61], v52 offset0:247 offset1:255
	s_waitcnt lgkmcnt(14)
	s_waitcnt lgkmcnt(13)
	s_waitcnt lgkmcnt(12)
	s_waitcnt lgkmcnt(11)
	s_waitcnt lgkmcnt(10)
	s_waitcnt lgkmcnt(9)
	s_waitcnt lgkmcnt(8)
	v_cvt_pk_bf16_f32 v15, v15, v17
	s_waitcnt lgkmcnt(6)
	s_waitcnt lgkmcnt(5)
	s_waitcnt lgkmcnt(4)
	s_waitcnt lgkmcnt(3)
	s_waitcnt lgkmcnt(1)
	v_cvt_pk_bf16_f32 v7, v12, v12
	v_cvt_pk_bf16_f32 v12, v14, v14
	v_cvt_pk_bf16_f32 v14, v16, v16
	v_cvt_pk_bf16_f32 v16, v18, v18
	v_cvt_pk_bf16_f32 v18, v20, v20
	v_cvt_pk_bf16_f32 v20, v22, v22
	s_waitcnt lgkmcnt(0)
	v_cvt_pk_bf16_f32 v10, v10, v10
	v_cvt_pk_bf16_f32 v22, v24, v24
	v_cvt_pk_bf16_f32 v13, v13, v13
	v_cvt_pk_bf16_f32 v24, v11, v11
	v_cvt_pk_bf16_f32 v17, v19, v19
	v_cvt_pk_bf16_f32 v19, v21, v21
	v_cvt_pk_bf16_f32 v21, v23, v23
	v_cvt_pk_bf16_f32 v23, v25, v25
	v_cvt_pk_bf16_f32 v25, v36, v36
	v_cvt_pk_bf16_f32 v36, v38, v38
	v_cvt_pk_bf16_f32 v38, v40, v40
	v_cvt_pk_bf16_f32 v40, v42, v42
	v_cvt_pk_bf16_f32 v55, v58, v58
	v_cvt_pk_bf16_f32 v37, v37, v37
	v_cvt_pk_bf16_f32 v39, v39, v39
	v_cvt_pk_bf16_f32 v43, v43, v43
	v_cvt_pk_bf16_f32 v58, v59, v59
	v_cvt_pk_bf16_f32 v34, v34, v34
	v_cvt_pk_bf16_f32 v42, v56, v56
	v_cvt_pk_bf16_f32 v56, v60, v60
	v_cvt_pk_bf16_f32 v35, v35, v35
	v_cvt_pk_bf16_f32 v41, v41, v41
	v_cvt_pk_bf16_f32 v57, v57, v57
	v_cvt_pk_bf16_f32 v59, v61, v61
	v_lshrrev_b32_e32 v60, 16, v13
	v_bfi_b32 v10, s33, v10, v7
	v_bfi_b32 v11, s33, v14, v12
	v_bfi_b32 v12, s33, v18, v16
	v_bfi_b32 v13, s33, v22, v20
	v_and_or_b32 v14, v24, s33, v60
	v_bfi_b32 v16, s33, v19, v17
	v_bfi_b32 v17, s33, v23, v21
	v_bfi_b32 v18, s33, v34, v25
	v_bfi_b32 v19, s33, v38, v36
	v_bfi_b32 v20, s33, v42, v40
	v_bfi_b32 v21, s33, v56, v55
	v_bfi_b32 v22, s33, v35, v37
	v_bfi_b32 v23, s33, v41, v39
	v_bfi_b32 v24, s33, v57, v43
	v_bfi_b32 v25, s33, v59, v58
	global_store_dwordx4 v[26:27], v[10:13], off
	global_store_dwordx4 v[28:29], v[14:17], off
	global_store_dwordx4 v[30:31], v[18:21], off
	global_store_dwordx4 v[32:33], v[22:25], off
	s_waitcnt lgkmcnt(0)
	s_cbranch_scc0 .LBB0_776

.LBB0_781:
	s_mul_hi_i32 s0, s20, 0x91a2b3c5
	s_add_i32 s0, s0, s20
	s_lshr_b32 s1, s0, 31
	s_ashr_i32 s0, s0, 11
	s_add_i32 s22, s0, s1
	s_mul_i32 s0, s22, 0xfffff1f0
	s_add_i32 s4, s20, s0
	s_ashr_i32 s23, s22, 31
	s_cmpk_gt_i32 s4, 0xa0f
	s_mov_b64 s[0:1], -1
	v_add_u32_e32 v27, 0x400, v20
	v_add_u32_e32 v26, 0x800, v20
	v_add_u32_e32 v25, 0xc00, v20
	v_add_u32_e32 v24, 0x1000, v20
	v_add_u32_e32 v23, 0x1400, v20
	v_add_u32_e32 v22, 0x1800, v20
	v_add_u32_e32 v21, 0x1c00, v20
	s_cbranch_scc0 .LBB0_783
	v_readlane_b32 s36, v252, 0
	s_lshl_b64 s[0:1], s[22:23], 23
	v_readlane_b32 s46, v252, 10
	v_readlane_b32 s47, v252, 11
	s_add_u32 s8, s46, s0
	s_addc_u32 s9, s47, s1
	s_lshl_b64 s[0:1], s[22:23], 22
	v_readlane_b32 s5, v250, 23
	s_add_u32 s5, s5, s0
	v_readlane_b32 s0, v250, 24
	s_addc_u32 s1, s0, s1
	s_add_i32 s0, s4, 0xf5f0
	s_lshl_b32 s6, s0, 1
	s_and_b32 s6, s6, 0x7fc0
	s_lshl_b32 s0, s0, 5
	v_or_b32_e32 v9, s6, v45
	s_and_b32 s0, s0, 0x3e0
	v_lshlrev_b32_e32 v9, 10, v9
	v_or3_b32 v9, v9, s0, v44
	v_lshlrev_b32_e32 v138, 2, v9
	v_lshl_add_u64 v[10:11], s[8:9], 0, v[138:139]
	v_add_co_u32_e32 v12, vcc, s68, v10
	global_load_dword v9, v138, s[8:9]
	s_nop 0
	v_addc_co_u32_e32 v13, vcc, 0, v11, vcc
	v_add_co_u32_e32 v14, vcc, s69, v10
	s_mov_b32 s7, 0x22000
	s_nop 0
	v_addc_co_u32_e32 v15, vcc, 0, v11, vcc
	v_add_co_u32_e32 v16, vcc, s70, v10
	s_lshl_b32 s6, s6, 1
	s_nop 0
	v_addc_co_u32_e32 v17, vcc, 0, v11, vcc
	v_add_co_u32_e32 v18, vcc, s19, v10
	s_add_u32 s6, s5, s6
	s_nop 0
	v_addc_co_u32_e32 v19, vcc, 0, v11, vcc
	v_add_co_u32_e32 v28, vcc, s10, v10
	v_readlane_b32 s37, v252, 1
	s_nop 0
	v_addc_co_u32_e32 v29, vcc, 0, v11, vcc
	v_add_co_u32_e32 v30, vcc, s27, v10
	v_readlane_b32 s38, v252, 2
	s_nop 0
	v_addc_co_u32_e32 v31, vcc, 0, v11, vcc
	v_add_co_u32_e32 v32, vcc, s16, v10
	v_readlane_b32 s39, v252, 3
	s_nop 0
	v_addc_co_u32_e32 v33, vcc, 0, v11, vcc
	v_add_co_u32_e32 v34, vcc, s31, v10
	v_readlane_b32 s40, v252, 4
	s_nop 0
	v_addc_co_u32_e32 v35, vcc, 0, v11, vcc
	global_load_dword v36, v[12:13], off nt
	global_load_dword v37, v[14:15], off nt
	global_load_dword v38, v[16:17], off nt
	global_load_dword v39, v[18:19], off nt
	global_load_dword v40, v[28:29], off nt
	global_load_dword v41, v[30:31], off nt
	global_load_dword v42, v[32:33], off nt
	global_load_dword v43, v[34:35], off nt
	v_add_co_u32_e32 v12, vcc, s35, v10
	v_readlane_b32 s41, v252, 5
	s_nop 0
	v_addc_co_u32_e32 v13, vcc, 0, v11, vcc
	v_add_co_u32_e32 v14, vcc, s18, v10
	v_readlane_b32 s42, v252, 6
	s_nop 0
	v_addc_co_u32_e32 v15, vcc, 0, v11, vcc
	v_add_co_u32_e32 v16, vcc, s34, v10
	v_readlane_b32 s43, v252, 7
	s_nop 0
	v_addc_co_u32_e32 v17, vcc, 0, v11, vcc
	v_add_co_u32_e32 v18, vcc, s52, v10
	v_readlane_b32 s44, v252, 8
	s_nop 0
	v_addc_co_u32_e32 v19, vcc, 0, v11, vcc
	v_add_co_u32_e32 v28, vcc, s30, v10
	v_readlane_b32 s45, v252, 9
	s_nop 0
	v_addc_co_u32_e32 v29, vcc, 0, v11, vcc
	v_add_co_u32_e32 v30, vcc, s17, v10
	v_readlane_b32 s48, v252, 12
	s_nop 0
	v_addc_co_u32_e32 v31, vcc, 0, v11, vcc
	v_add_co_u32_e32 v32, vcc, s90, v10
	v_readlane_b32 s49, v252, 13
	s_nop 0
	v_addc_co_u32_e32 v33, vcc, 0, v11, vcc
	v_add_co_u32_e32 v34, vcc, s91, v10
	v_readlane_b32 s50, v252, 14
	s_nop 0
	v_addc_co_u32_e32 v35, vcc, 0, v11, vcc
	global_load_dword v50, v[12:13], off nt
	global_load_dword v51, v[14:15], off nt
	global_load_dword v52, v[16:17], off nt
	global_load_dword v53, v[18:19], off nt
	global_load_dword v55, v[28:29], off nt
	global_load_dword v56, v[30:31], off nt
	global_load_dword v57, v[32:33], off nt
	global_load_dword v58, v[34:35], off nt
	v_add_co_u32_e32 v12, vcc, s7, v10
	s_mov_b32 s7, 0x24000
	s_nop 0
	v_addc_co_u32_e32 v13, vcc, 0, v11, vcc
	v_add_co_u32_e32 v14, vcc, s7, v10
	s_mov_b32 s7, 0x26000
	s_nop 0
	v_addc_co_u32_e32 v15, vcc, 0, v11, vcc
	v_add_co_u32_e32 v16, vcc, s7, v10
	s_mov_b32 s7, 0x28000
	s_nop 0
	v_addc_co_u32_e32 v17, vcc, 0, v11, vcc
	v_add_co_u32_e32 v18, vcc, s7, v10
	s_mov_b32 s7, 0x2a000
	s_nop 0
	v_addc_co_u32_e32 v19, vcc, 0, v11, vcc
	v_add_co_u32_e32 v28, vcc, s7, v10
	s_mov_b32 s7, 0x2c000
	s_nop 0
	v_addc_co_u32_e32 v29, vcc, 0, v11, vcc
	v_add_co_u32_e32 v30, vcc, s7, v10
	s_mov_b32 s7, 0x2e000
	s_nop 0
	v_addc_co_u32_e32 v31, vcc, 0, v11, vcc
	v_add_co_u32_e32 v32, vcc, s7, v10
	s_mov_b32 s7, 0x30000
	s_nop 0
	v_addc_co_u32_e32 v33, vcc, 0, v11, vcc
	v_add_co_u32_e32 v34, vcc, s7, v10
	s_mov_b32 s7, 0x32000
	s_nop 0
	v_addc_co_u32_e32 v35, vcc, 0, v11, vcc
	global_load_dword v59, v[12:13], off nt
	global_load_dword v60, v[14:15], off nt
	global_load_dword v61, v[16:17], off nt
	global_load_dword v62, v[18:19], off nt
	global_load_dword v63, v[28:29], off nt
	global_load_dword v64, v[30:31], off nt
	s_nop 0
	global_load_dword v32, v[32:33], off nt
	s_nop 0
	global_load_dword v33, v[34:35], off nt
	v_add_co_u32_e32 v12, vcc, s7, v10
	s_mov_b32 s7, 0x34000
	s_nop 0
	v_addc_co_u32_e32 v13, vcc, 0, v11, vcc
	v_add_co_u32_e32 v14, vcc, s7, v10
	s_mov_b32 s7, 0x36000
	s_nop 0
	v_addc_co_u32_e32 v15, vcc, 0, v11, vcc
	v_add_co_u32_e32 v16, vcc, s7, v10
	s_mov_b32 s7, 0x38000
	s_nop 0
	v_addc_co_u32_e32 v17, vcc, 0, v11, vcc
	v_add_co_u32_e32 v18, vcc, s7, v10
	s_mov_b32 s7, 0x3a000
	s_nop 0
	v_addc_co_u32_e32 v19, vcc, 0, v11, vcc
	v_add_co_u32_e32 v28, vcc, s7, v10
	s_mov_b32 s7, 0x3c000
	s_nop 0
	v_addc_co_u32_e32 v29, vcc, 0, v11, vcc
	v_add_co_u32_e32 v30, vcc, s7, v10
	s_mov_b32 s7, 0x3e000
	s_nop 0
	v_addc_co_u32_e32 v31, vcc, 0, v11, vcc
	v_add_co_u32_e32 v10, vcc, s7, v10
	s_addc_u32 s7, s1, 0
	s_nop 0
	v_addc_co_u32_e32 v11, vcc, 0, v11, vcc
	global_load_dword v12, v[12:13], off nt
	s_nop 0
	global_load_dword v13, v[14:15], off nt
	s_nop 0
	global_load_dword v14, v[16:17], off nt
	global_load_dword v15, v[18:19], off nt
	s_nop 0
	global_load_dword v16, v[28:29], off nt
	global_load_dword v17, v[30:31], off nt
	s_nop 0
	global_load_dword v10, v[10:11], off nt
	s_waitcnt vmcnt(0)
	ds_write2_b32 v20, v9, v36 offset1:66
	ds_write2_b32 v20, v37, v38 offset0:132 offset1:198
	ds_write2_b32 v27, v39, v40 offset0:8 offset1:74
	ds_write2_b32 v27, v41, v42 offset0:140 offset1:206
	ds_write2_b32 v26, v43, v50 offset0:16 offset1:82
	ds_write2_b32 v26, v51, v52 offset0:148 offset1:214
	ds_write2_b32 v25, v53, v55 offset0:24 offset1:90
	ds_write2_b32 v25, v56, v57 offset0:156 offset1:222
	ds_write2_b32 v24, v58, v59 offset0:32 offset1:98
	ds_write2_b32 v24, v60, v61 offset0:164 offset1:230
	ds_write2_b32 v23, v62, v63 offset0:40 offset1:106
	ds_write2_b32 v23, v64, v32 offset0:172 offset1:238
	ds_write2_b32 v22, v33, v12 offset0:48 offset1:114
	ds_write2_b32 v22, v13, v14 offset0:180 offset1:246
	ds_write2_b32 v21, v15, v16 offset0:56 offset1:122
	ds_write2_b32 v21, v17, v10 offset0:188 offset1:254
	s_waitcnt lgkmcnt(0)
	ds_read2_b32 v[14:15], v7 offset1:8
	ds_read2_b32 v[18:19], v7 offset0:33 offset1:41
	ds_read2_b32 v[28:29], v7 offset0:66 offset1:74
	v_mov_b32_e32 v9, v139
	ds_read2_b32 v[30:31], v7 offset0:99 offset1:107
	v_lshl_add_u64 v[16:17], s[6:7], 0, v[8:9]
	s_waitcnt lgkmcnt(3)
	s_waitcnt lgkmcnt(2)
	v_cvt_pk_bf16_f32 v10, v14, v18
	ds_read2_b32 v[32:33], v7 offset0:132 offset1:140
	ds_read2_b32 v[34:35], v7 offset0:165 offset1:173
	s_waitcnt lgkmcnt(3)
	s_waitcnt lgkmcnt(2)
	v_cvt_pk_bf16_f32 v11, v28, v30
	ds_read2_b32 v[36:37], v7 offset0:198 offset1:206
	ds_read2_b32 v[38:39], v7 offset0:231 offset1:239
	s_waitcnt lgkmcnt(3)
	s_waitcnt lgkmcnt(2)
	v_cvt_pk_bf16_f32 v12, v32, v34
	s_waitcnt lgkmcnt(1)
	s_waitcnt lgkmcnt(0)
	v_cvt_pk_bf16_f32 v13, v36, v38
	v_or_b32_e32 v9, s0, v46
	v_lshlrev_b32_e32 v138, 12, v9
	v_lshl_add_u64 v[40:41], v[16:17], 0, v[138:139]
	global_store_dwordx4 v[40:41], v[10:13], off
	s_nop 1
	v_cvt_pk_bf16_f32 v10, v15, v19
	s_nop 0
	v_cvt_pk_bf16_f32 v11, v29, v31
	v_cvt_pk_bf16_f32 v12, v33, v35
	v_cvt_pk_bf16_f32 v13, v37, v39
	v_or_b32_e32 v9, s0, v47
	v_lshlrev_b32_e32 v138, 12, v9
	ds_read2_b32 v[14:15], v7 offset0:16 offset1:24
	v_lshl_add_u64 v[18:19], v[16:17], 0, v[138:139]
	global_store_dwordx4 v[18:19], v[10:13], off
	ds_read2_b32 v[18:19], v7 offset0:49 offset1:57
	ds_read2_b32 v[28:29], v7 offset0:82 offset1:90
	ds_read2_b32 v[30:31], v7 offset0:115 offset1:123
	s_waitcnt lgkmcnt(3)
	s_waitcnt lgkmcnt(2)
	v_cvt_pk_bf16_f32 v10, v14, v18
	ds_read2_b32 v[32:33], v7 offset0:148 offset1:156
	ds_read2_b32 v[34:35], v7 offset0:181 offset1:189
	s_waitcnt lgkmcnt(3)
	s_waitcnt lgkmcnt(2)
	v_cvt_pk_bf16_f32 v11, v28, v30
	ds_read2_b32 v[36:37], v7 offset0:214 offset1:222
	ds_read2_b32 v[38:39], v7 offset0:247 offset1:255
	s_waitcnt lgkmcnt(3)
	s_waitcnt lgkmcnt(2)
	v_cvt_pk_bf16_f32 v12, v32, v34
	s_waitcnt lgkmcnt(1)
	s_waitcnt lgkmcnt(0)
	v_cvt_pk_bf16_f32 v13, v36, v38
	v_or_b32_e32 v9, s0, v48
	v_lshlrev_b32_e32 v138, 12, v9
	v_lshl_add_u64 v[40:41], v[16:17], 0, v[138:139]
	global_store_dwordx4 v[40:41], v[10:13], off
	s_nop 1
	v_cvt_pk_bf16_f32 v10, v15, v19
	s_nop 0
	v_cvt_pk_bf16_f32 v11, v29, v31
	v_cvt_pk_bf16_f32 v12, v33, v35
	v_cvt_pk_bf16_f32 v13, v37, v39
	v_or_b32_e32 v9, s0, v49
	v_lshlrev_b32_e32 v138, 12, v9
	v_lshl_add_u64 v[14:15], v[16:17], 0, v[138:139]
	global_store_dwordx4 v[14:15], v[10:13], off
	s_waitcnt lgkmcnt(0)
	v_readlane_b32 s51, v252, 15
	s_cbranch_execnz .LBB0_780
	s_branch .LBB0_784

.LBB0_830:
.LBB0_831:
	s_andn2_saveexec_b64 s[0:1], s[0:1]
	v_add_u32_e32 v10, 0x200, v9
	s_or_b64 exec, exec, s[0:1]
	v_readlane_b32 s36, v252, 22
	s_mul_i32 s1, s22, 0x1418000
	v_readlane_b32 s40, v252, 26
	s_mul_hi_i32 s0, s22, 0x1418000
	v_readlane_b32 s41, v252, 27
	s_add_u32 s6, s40, s1
	s_addc_u32 s7, s41, s0
	s_lshl_b32 s0, s22, 10
	s_ashr_i32 s1, s0, 31
	v_readlane_b32 s38, v252, 24
	s_lshl_b64 s[0:1], s[0:1], 2
	v_readlane_b32 s39, v252, 25
	s_add_u32 s28, s38, s0
	s_sext_i32_i16 s0, s5
	s_addc_u32 s29, s39, s1
	s_lshl_b32 s24, s0, 6
	v_cmp_lt_i32_e64 s[0:1], -1, v10
	v_or_b32_e32 v9, s24, v45
	v_mul_i32_i24_e32 v12, 0x5060, v9
	v_cndmask_b32_e64 v138, 0, v10, s[0:1]
	v_lshl_add_u64 v[10:11], v[138:139], 2, s[6:7]
	v_ashrrev_i32_e32 v13, 31, v12
	v_lshl_add_u64 v[10:11], v[10:11], 0, v[12:13]
	s_mov_b32 s5, 0xa000
	v_add_co_u32_e32 v12, vcc, s5, v10
	s_mov_b32 s5, 0x28000
	s_nop 0
	v_addc_co_u32_e32 v13, vcc, 0, v11, vcc
	v_add_co_u32_e32 v14, vcc, s18, v10
	v_readlane_b32 s37, v252, 23
	s_nop 0
	v_addc_co_u32_e32 v15, vcc, 0, v11, vcc
	v_add_co_u32_e32 v16, vcc, s90, v10
	s_mov_b32 s10, 0xa000
	s_nop 0
	v_addc_co_u32_e32 v17, vcc, 0, v11, vcc
	v_add_co_u32_e32 v18, vcc, s5, v10
	s_mov_b32 s5, 0x32000
	s_nop 0
	v_addc_co_u32_e32 v19, vcc, 0, v11, vcc
	v_add_co_u32_e32 v36, vcc, s5, v10
	s_mov_b32 s5, 0x3c000
	s_nop 0
	v_addc_co_u32_e32 v37, vcc, 0, v11, vcc
	v_add_co_u32_e32 v38, vcc, s5, v10
	s_mov_b32 s5, 0x46000
	s_nop 0
	v_addc_co_u32_e32 v39, vcc, 0, v11, vcc
	v_add_co_u32_e32 v40, vcc, s5, v10
	s_mov_b32 s5, 0x50000
	s_nop 0
	v_addc_co_u32_e32 v41, vcc, 0, v11, vcc
	global_load_dword v33, v[10:11], off nt
	global_load_dword v34, v[12:13], off offset:192 nt
	global_load_dword v30, v[14:15], off offset:384 nt
	global_load_dword v31, v[16:17], off offset:576 nt
	global_load_dword v28, v[18:19], off offset:768 nt
	global_load_dword v29, v[36:37], off offset:960 nt
	global_load_dword v9, v[38:39], off offset:1152 nt
	global_load_dword v32, v[40:41], off offset:1344 nt
	v_add_co_u32_e32 v12, vcc, s5, v10
	s_mov_b32 s5, 0x5a000
	s_nop 0
	v_addc_co_u32_e32 v13, vcc, 0, v11, vcc
	v_add_co_u32_e32 v14, vcc, s5, v10
	s_mov_b32 s5, 0x64000
	s_nop 0
	v_addc_co_u32_e32 v15, vcc, 0, v11, vcc
	v_add_co_u32_e32 v16, vcc, s5, v10
	s_mov_b32 s5, 0x6e000
	s_nop 0
	v_addc_co_u32_e32 v17, vcc, 0, v11, vcc
	v_add_co_u32_e32 v18, vcc, s5, v10
	s_mov_b32 s5, 0x78000
	s_nop 0
	v_addc_co_u32_e32 v19, vcc, 0, v11, vcc
	v_add_co_u32_e32 v36, vcc, s5, v10
	s_mov_b32 s5, 0x82000
	s_nop 0
	v_addc_co_u32_e32 v37, vcc, 0, v11, vcc
	v_add_co_u32_e32 v50, vcc, s5, v10
	s_mov_b32 s5, 0x8c000
	s_nop 0
	v_addc_co_u32_e32 v51, vcc, 0, v11, vcc
	v_add_co_u32_e32 v52, vcc, s5, v10
	s_mov_b32 s5, 0x96000
	s_nop 0
	v_addc_co_u32_e32 v53, vcc, 0, v11, vcc
	v_add_co_u32_e32 v56, vcc, s5, v10
	s_mov_b32 s5, 0xa0000
	s_nop 0
	v_addc_co_u32_e32 v57, vcc, 0, v11, vcc
	global_load_dword v41, v[12:13], off offset:1536 nt
	global_load_dword v42, v[14:15], off offset:1728 nt
	global_load_dword v38, v[16:17], off offset:1920 nt
	global_load_dword v39, v[18:19], off offset:2112 nt
	s_nop 0
	global_load_dword v36, v[36:37], off offset:2304 nt
	s_nop 0
	global_load_dword v37, v[50:51], off offset:2496 nt
	global_load_dword v35, v[52:53], off offset:2688 nt
	global_load_dword v40, v[56:57], off offset:2880 nt
	v_add_co_u32_e32 v12, vcc, s5, v10
	s_mov_b32 s5, 0xaa000
	s_nop 0
	v_addc_co_u32_e32 v13, vcc, 0, v11, vcc
	v_add_co_u32_e32 v14, vcc, s5, v10
	s_mov_b32 s5, 0xb4000
	s_nop 0
	v_addc_co_u32_e32 v15, vcc, 0, v11, vcc
	v_add_co_u32_e32 v16, vcc, s5, v10
	s_mov_b32 s5, 0xbe000
	s_nop 0
	v_addc_co_u32_e32 v17, vcc, 0, v11, vcc
	v_add_co_u32_e32 v18, vcc, s5, v10
	s_mov_b32 s5, 0xc8000
	s_nop 0
	v_addc_co_u32_e32 v19, vcc, 0, v11, vcc
	v_add_co_u32_e32 v50, vcc, s5, v10
	s_mov_b32 s5, 0xd2000
	s_nop 0
	v_addc_co_u32_e32 v51, vcc, 0, v11, vcc
	v_add_co_u32_e32 v58, vcc, s5, v10
	s_mov_b32 s5, 0xdd000
	s_nop 0
	v_addc_co_u32_e32 v59, vcc, 0, v11, vcc
	v_add_co_u32_e32 v60, vcc, s5, v10
	s_mov_b32 s5, 0xe7000
	s_nop 0
	v_addc_co_u32_e32 v61, vcc, 0, v11, vcc
	v_add_co_u32_e32 v62, vcc, s5, v10
	s_mov_b32 s5, 0xf1000
	s_nop 0
	v_addc_co_u32_e32 v63, vcc, 0, v11, vcc
	global_load_dword v56, v[12:13], off offset:3072 nt
	global_load_dword v57, v[14:15], off offset:3264 nt
	global_load_dword v52, v[16:17], off offset:3456 nt
	global_load_dword v53, v[18:19], off offset:3648 nt
	s_nop 0
	global_load_dword v50, v[50:51], off offset:3840 nt
	s_nop 0
	global_load_dword v51, v[58:59], off offset:4032 nt
	global_load_dword v43, v[60:61], off offset:128 nt
	global_load_dword v55, v[62:63], off offset:320 nt
	v_add_co_u32_e32 v12, vcc, s5, v10
	s_mov_b32 s5, 0xfb000
	s_nop 0
	v_addc_co_u32_e32 v13, vcc, 0, v11, vcc
	v_add_co_u32_e32 v14, vcc, s5, v10
	s_mov_b32 s5, 0x105000
	s_nop 0
	v_addc_co_u32_e32 v15, vcc, 0, v11, vcc
	v_add_co_u32_e32 v16, vcc, s5, v10
	s_mov_b32 s5, 0x10f000
	s_nop 0
	v_addc_co_u32_e32 v17, vcc, 0, v11, vcc
	v_add_co_u32_e32 v18, vcc, s5, v10
	s_mov_b32 s5, 0x119000
	s_nop 0
	v_addc_co_u32_e32 v19, vcc, 0, v11, vcc
	v_add_co_u32_e32 v58, vcc, s5, v10
	s_mov_b32 s5, 0x123000
	s_nop 0
	v_addc_co_u32_e32 v59, vcc, 0, v11, vcc
	v_add_co_u32_e32 v66, vcc, s5, v10
	v_readlane_b32 s42, v252, 28
	s_nop 0
	v_addc_co_u32_e32 v67, vcc, 0, v11, vcc
	v_add_co_u32_e32 v68, vcc, 0x12d000, v10
	v_readlane_b32 s43, v252, 29
	s_nop 0
	v_addc_co_u32_e32 v69, vcc, 0, v11, vcc
	v_add_co_u32_e32 v10, vcc, 0x137000, v10
	v_readlane_b32 s44, v252, 30
	s_nop 0
	v_addc_co_u32_e32 v11, vcc, 0, v11, vcc
	global_load_dword v64, v[12:13], off offset:512 nt
	global_load_dword v65, v[14:15], off offset:704 nt
	global_load_dword v61, v[16:17], off offset:896 nt
	global_load_dword v62, v[18:19], off offset:1088 nt
	s_nop 0
	global_load_dword v59, v[58:59], off offset:1280 nt
	s_nop 0
	global_load_dword v60, v[66:67], off offset:1472 nt
	global_load_dword v58, v[68:69], off offset:1664 nt
	global_load_dword v63, v[10:11], off offset:1856 nt
	v_or_b32_e32 v18, s24, v6
	v_cndmask_b32_e64 v11, 0, 1, s[14:15]
	v_mov_b32_e32 v10, 1.0
	v_cmp_ne_u32_e64 s[36:37], 1, v11
	s_andn2_b64 vcc, exec, s[14:15]
	v_ashrrev_i32_e32 v19, 31, v18
	v_mov_b32_e32 v12, 1.0
	v_readlane_b32 s45, v252, 31
	v_readlane_b32 s46, v252, 32
	v_readlane_b32 s47, v252, 33
	v_readlane_b32 s48, v252, 34
	v_readlane_b32 s49, v252, 35
	v_readlane_b32 s50, v252, 36
	v_readlane_b32 s51, v252, 37
	s_cbranch_vccnz .LBB0_835
	v_lshl_add_u64 v[12:13], v[18:19], 2, s[28:29]
	global_load_dword v12, v[12:13], off nt
.LBB0_835:
	s_and_b64 vcc, exec, s[36:37]
	s_cbranch_vccnz .LBB0_837
	v_lshl_add_u64 v[10:11], v[18:19], 2, s[28:29]
	global_load_dword v10, v[10:11], off offset:4 nt
.LBB0_837:
	v_mov_b32_e32 v11, 1.0
	s_and_b64 vcc, exec, s[36:37]
	v_mov_b32_e32 v13, 1.0
	s_cbranch_vccnz .LBB0_839
	v_lshl_add_u64 v[14:15], v[18:19], 2, s[28:29]
	global_load_dword v13, v[14:15], off offset:8 nt
.LBB0_839:
	s_and_b64 vcc, exec, s[36:37]
	s_cbranch_vccnz .LBB0_841
	v_lshl_add_u64 v[14:15], v[18:19], 2, s[28:29]
	global_load_dword v11, v[14:15], off offset:12 nt
.LBB0_841:
	v_mov_b32_e32 v14, 1.0
	s_and_b64 vcc, exec, s[36:37]
	v_mov_b32_e32 v16, 1.0
	s_cbranch_vccnz .LBB0_843
	v_lshl_add_u64 v[16:17], v[18:19], 2, s[28:29]
	global_load_dword v16, v[16:17], off offset:16 nt
.LBB0_843:
	s_and_b64 vcc, exec, s[36:37]
	s_cbranch_vccnz .LBB0_845
	v_lshl_add_u64 v[14:15], v[18:19], 2, s[28:29]
	global_load_dword v14, v[14:15], off offset:20 nt
.LBB0_845:
	v_mov_b32_e32 v15, 1.0
	s_and_b64 vcc, exec, s[36:37]
	v_mov_b32_e32 v17, 1.0
	s_cbranch_vccnz .LBB0_847
	v_lshl_add_u64 v[66:67], v[18:19], 2, s[28:29]
	global_load_dword v17, v[66:67], off offset:24 nt
.LBB0_847:
	s_and_b64 vcc, exec, s[36:37]
	s_cbranch_vccnz .LBB0_779
	v_lshl_add_u64 v[18:19], v[18:19], 2, s[28:29]
	global_load_dword v15, v[18:19], off offset:28 nt
	s_branch .LBB0_779
